# attention tile loops (cross/retention/diff): full lgkmcnt(0) drains replaced by counted lgkmcnt ladders computed per consumer
# speedup vs baseline: 1.0305x; 1.0019x over previous
; #define AT_SLOAD(bi_, sl_) do { _Pragma("unroll") for (int x_ = 0; x_ < NBB; ++x_) _Pragma("unroll") for (int kk = 0; kk < KD; ++kk) \
;                     kfr[sl_][x_][kk] = *(const LAS bf16x8*)(Ks + (((bi_) * NBB + x_) * 16 + r) * KSTR + mp * D + kk * 32 + g4 * 8); } while (0)
; template <int D, int DV, int MODE, int NMAP, int KT> ...
;     ...
;                 AT_SLOAD(0, 0);
; #pragma unroll
;                 for (int bi = 0; bi < NSB; ++bi) {
;                     if (bi + 1 < NSB) AT_SLOAD(bi + 1, (bi + 1) & 1);
;                     __builtin_amdgcn_sched_barrier(0);
;                     __builtin_amdgcn_s_setprio(1);
; #pragma unroll
;                     for (int x_ = 0; x_ < NBB; ++x_) { const int nb = bi * NBB + x_;
;                         s[nb] = __builtin_amdgcn_mfma_f32_16x16x32_bf16(kfr[bi & 1][x_][0], qf[mp][0], (f32x4){0.f, 0.f, 0.f, 0.f}, 0, 0, 0);
; #pragma unroll
;                         for (int kk = 1; kk < KD; ++kk) s[nb] = __builtin_amdgcn_mfma_f32_16x16x32_bf16(kfr[bi & 1][x_][kk], qf[mp][kk], s[nb], 0, 0, 0); }
;                     __builtin_amdgcn_s_setprio(0);
;                     __builtin_amdgcn_sched_barrier(0);
;                 }
;     ...
;                     const float rowf = __builtin_amdgcn_exp2f(l2g * (float)(myrow - kt * KT));
; #pragma unroll
;                     for (int nb = 0; nb < NB; ++nb)
; #pragma unroll
;                         for (int j = 0; j < 4; ++j) { float p = s[nb][j] * (rowf * ck[nb][j]); if (diag && (kt * KT + nb * 16 + g4 * 4 + j > myrow)) p = 0.f; s[nb][j] = p; }
.LBB0_795:
	s_cmp_gt_i32 s19, s33
	s_cbranch_scc1 .LBB0_797
	s_bitcmp1_b32 s16, 0
	s_cselect_b32 s16, 0xd000, 0
	s_add_i32 s40, s16, 0
	v_lshlrev_b32_e32 v135, 1, v87
	v_add_u32_e32 v184, s40, v135
	v_add_u32_e32 v156, v184, v123
	ds_read_b128 v[66:69], v156
	ds_read_b128 v[70:73], v156 offset:64
	ds_read_b128 v[136:139], v156 offset:2304
	ds_read_b128 v[140:143], v156 offset:2368
	ds_read_b128 v[144:147], v156 offset:4608
	ds_read_b128 v[148:151], v156 offset:4672
	ds_read_b128 v[152:155], v156 offset:6912
	ds_read_b128 v[156:159], v156 offset:6976
	v_add3_u32 v135, s40, v123, v135
	ds_read_b128 v[160:163], v135 offset:9216
	ds_read_b128 v[164:167], v135 offset:9280
	v_add_u32_e32 v135, v184, v124
	ds_read_b128 v[168:171], v135 offset:9216
	ds_read_b128 v[172:175], v135 offset:9280
	v_add_u32_e32 v135, v184, v125
	ds_read_b128 v[176:179], v135 offset:9216
	ds_read_b128 v[180:183], v135 offset:9280
	v_add_u32_e32 v135, v184, v126
	ds_read_b128 v[194:197], v135 offset:9216
	ds_read_b128 v[198:201], v135 offset:9280
	s_add_i32 s16, s19, 0x7f
	s_setprio 1
	s_waitcnt lgkmcnt(14)
	v_mfma_f32_16x16x32_bf16 v[66:69], v[66:69], v[34:37], 0
	v_mfma_f32_16x16x32_bf16 v[66:69], v[70:73], v[38:41], v[66:69]
	s_waitcnt lgkmcnt(13)
	v_mfma_f32_16x16x32_bf16 v[70:73], v[136:139], v[34:37], 0
	s_waitcnt lgkmcnt(12)
	v_mfma_f32_16x16x32_bf16 v[70:73], v[140:143], v[38:41], v[70:73]
	s_waitcnt lgkmcnt(11)
	v_mfma_f32_16x16x32_bf16 v[136:139], v[144:147], v[34:37], 0
	s_waitcnt lgkmcnt(9)
	v_mfma_f32_16x16x32_bf16 v[140:143], v[152:155], v[34:37], 0
	v_mfma_f32_16x16x32_bf16 v[136:139], v[148:151], v[38:41], v[136:139]
	s_waitcnt lgkmcnt(8)
	v_mfma_f32_16x16x32_bf16 v[140:143], v[156:159], v[38:41], v[140:143]
	s_setprio 0
	s_setprio 1
	s_waitcnt lgkmcnt(7)
	v_mfma_f32_16x16x32_bf16 v[144:147], v[160:163], v[34:37], 0
	s_waitcnt lgkmcnt(5)
	v_mfma_f32_16x16x32_bf16 v[148:151], v[168:171], v[34:37], 0
	s_waitcnt lgkmcnt(3)
	v_mfma_f32_16x16x32_bf16 v[152:155], v[176:179], v[34:37], 0
	s_waitcnt lgkmcnt(1)
	v_mfma_f32_16x16x32_bf16 v[156:159], v[194:197], v[34:37], 0
	v_mfma_f32_16x16x32_bf16 v[144:147], v[164:167], v[38:41], v[144:147]
	v_mfma_f32_16x16x32_bf16 v[148:151], v[172:175], v[38:41], v[148:151]
	v_mfma_f32_16x16x32_bf16 v[152:155], v[180:183], v[38:41], v[152:155]
	s_waitcnt lgkmcnt(0)
	v_mfma_f32_16x16x32_bf16 v[156:159], v[198:201], v[38:41], v[156:159]
	s_setprio 0
	v_cvt_f32_i32_e32 v135, v134
	s_cmp_gt_i32 s16, s31
	v_add_u32_e32 v160, s19, v89
	s_cselect_b64 s[16:17], -1, 0
	v_mul_f32_e32 v135, v88, v135
	v_exp_f32_e32 v135, v135
	v_cmp_gt_i32_e32 vcc, v160, v122
	s_and_b64 s[42:43], s[16:17], vcc
	v_cmp_ge_i32_e32 vcc, v160, v122
	v_mul_f32_e32 v161, v90, v135
	v_mul_f32_e32 v66, v161, v66
	v_mul_f32_e32 v161, v92, v135
	v_mul_f32_e32 v68, v161, v68
	v_add_u32_e32 v161, 2, v160
	v_mul_f32_e32 v162, v91, v135
	v_cndmask_b32_e64 v66, v66, 0, s[42:43]
	s_and_b64 s[42:43], s[16:17], vcc
	v_cmp_gt_i32_e32 vcc, v161, v122
	v_mul_f32_e32 v161, v93, v135
	v_mul_f32_e32 v67, v162, v67
	v_mul_f32_e32 v69, v161, v69
	v_add_u32_e32 v161, 3, v160
	v_cndmask_b32_e64 v67, v67, 0, s[42:43]
	s_and_b64 s[42:43], s[16:17], vcc
	v_cmp_gt_i32_e32 vcc, v161, v122
	v_add_u32_e32 v161, 16, v160
	v_cndmask_b32_e64 v68, v68, 0, s[42:43]
	s_and_b64 s[42:43], s[16:17], vcc
	v_cmp_gt_i32_e32 vcc, v161, v122
	v_mul_f32_e32 v161, v95, v135
	v_mul_f32_e32 v71, v161, v71
	v_add_u32_e32 v161, 17, v160
	v_cndmask_b32_e64 v69, v69, 0, s[42:43]
	v_mul_f32_e32 v162, v94, v135
	s_and_b64 s[42:43], s[16:17], vcc
	v_cmp_gt_i32_e32 vcc, v161, v122
	v_mul_f32_e32 v161, v96, v135
	v_mul_f32_e32 v70, v162, v70
	v_mul_f32_e32 v72, v161, v72
	v_add_u32_e32 v161, 18, v160
	v_cndmask_b32_e64 v70, v70, 0, s[42:43]
	s_and_b64 s[42:43], s[16:17], vcc
	v_cmp_gt_i32_e32 vcc, v161, v122
	v_mul_f32_e32 v161, v97, v135
	v_mul_f32_e32 v73, v161, v73
	v_add_u32_e32 v161, 19, v160
	v_cndmask_b32_e64 v71, v71, 0, s[42:43]
	s_and_b64 s[42:43], s[16:17], vcc
	v_cmp_gt_i32_e32 vcc, v161, v122
	v_add_u32_e32 v161, 32, v160
	v_cndmask_b32_e64 v72, v72, 0, s[42:43]
	s_and_b64 s[42:43], s[16:17], vcc
	v_mul_f32_e32 v162, v98, v135
	v_cmp_gt_i32_e32 vcc, v161, v122
	v_cndmask_b32_e64 v73, v73, 0, s[42:43]
	v_mul_f32_e32 v136, v162, v136
	s_and_b64 s[42:43], s[16:17], vcc
	v_cndmask_b32_e64 v161, v136, 0, s[42:43]
	v_mul_f32_e32 v136, v99, v135
	v_mul_f32_e32 v136, v136, v137
	v_add_u32_e32 v137, 33, v160
	v_cmp_gt_i32_e32 vcc, v137, v122
	s_and_b64 s[42:43], s[16:17], vcc
	v_add_u32_e32 v137, 34, v160
	v_cndmask_b32_e64 v162, v136, 0, s[42:43]
	v_mul_f32_e32 v136, v100, v135
	v_cmp_gt_i32_e32 vcc, v137, v122
	v_mul_f32_e32 v136, v136, v138
	s_and_b64 s[42:43], s[16:17], vcc
	v_add_u32_e32 v137, 35, v160
	v_cndmask_b32_e64 v163, v136, 0, s[42:43]
	v_mul_f32_e32 v136, v101, v135
	v_cmp_gt_i32_e32 vcc, v137, v122
	v_mul_f32_e32 v136, v136, v139
	s_and_b64 s[42:43], s[16:17], vcc
	v_cndmask_b32_e64 v164, v136, 0, s[42:43]
	v_add_u32_e32 v136, 48, v160
	v_mul_f32_e32 v137, v102, v135
	v_cmp_gt_i32_e32 vcc, v136, v122
	v_mul_f32_e32 v137, v137, v140
	s_and_b64 s[42:43], s[16:17], vcc
	v_cndmask_b32_e64 v165, v137, 0, s[42:43]
	v_add_u32_e32 v137, 49, v160
	v_mul_f32_e32 v136, v103, v135
	v_cmp_gt_i32_e32 vcc, v137, v122
	v_mul_f32_e32 v136, v136, v141
	s_and_b64 s[42:43], s[16:17], vcc
	v_add_u32_e32 v137, 50, v160
	v_cndmask_b32_e64 v166, v136, 0, s[42:43]
	v_mul_f32_e32 v136, v104, v135
	v_cmp_gt_i32_e32 vcc, v137, v122
	v_mul_f32_e32 v136, v136, v142
	s_and_b64 s[42:43], s[16:17], vcc
	v_add_u32_e32 v137, 51, v160
	v_cndmask_b32_e64 v167, v136, 0, s[42:43]
	v_mul_f32_e32 v136, v105, v135
	v_cmp_gt_i32_e32 vcc, v137, v122
; __device__ __forceinline__ unsigned cvt_pk_bf16(float lo, float hi) { unsigned r; asm volatile("v_cvt_pk_bf16_f32 %0, %1, %2" : "=v"(r) : "v"(lo), "v"(hi)); return r; }
; template <int D, int DV, int MODE, int NMAP, int KT> ...
;     ...
;                     const float rowf = __builtin_amdgcn_exp2f(l2g * (float)(myrow - kt * KT));
; #pragma unroll
;                     for (int nb = 0; nb < NB; ++nb)
; #pragma unroll
;                         for (int j = 0; j < 4; ++j) { float p = s[nb][j] * (rowf * ck[nb][j]); if (diag && (kt * KT + nb * 16 + g4 * 4 + j > myrow)) p = 0.f; s[nb][j] = p; }
;                 }
; #pragma unroll
;                 for (int kk = 0; kk < KK2; ++kk) { u32x4 wv; wv.x = cvt_pk_bf16(s[2 * kk][0], s[2 * kk][1]); wv.y = cvt_pk_bf16(s[2 * kk][2], s[2 * kk][3]);
;                     wv.z = cvt_pk_bf16(s[2 * kk + 1][0], s[2 * kk + 1][1]); wv.w = cvt_pk_bf16(s[2 * kk + 1][2], s[2 * kk + 1][3]); pb[mp][kk] = __builtin_bit_cast(bf16x8, wv); }
;             }
;             {
;                 constexpr int CBB = 4, NCB = (DV / 16) / CBB, NVB = KK2 * NCB;
;                 bf16x8 vfr[2][CBB];
;     ...
;                 AT_VLOAD(0, 0);
; #pragma unroll
;                 for (int b_ = 0; b_ < NVB; ++b_) {
;                     if (b_ + 1 < NVB) AT_VLOAD(b_ + 1, (b_ + 1) & 1);
	v_mul_f32_e32 v136, v136, v143
	s_and_b64 s[42:43], s[16:17], vcc
	v_cndmask_b32_e64 v143, v136, 0, s[42:43]
	v_add_u32_e32 v136, 64, v160
	v_mul_f32_e32 v137, v106, v135
	v_cmp_gt_i32_e32 vcc, v136, v122
	v_mul_f32_e32 v137, v137, v144
	s_and_b64 s[42:43], s[16:17], vcc
	v_cndmask_b32_e64 v144, v137, 0, s[42:43]
	v_add_u32_e32 v137, 0x41, v160
	v_mul_f32_e32 v136, v107, v135
	v_cmp_gt_i32_e32 vcc, v137, v122
	v_mul_f32_e32 v136, v136, v145
	s_and_b64 s[42:43], s[16:17], vcc
	v_add_u32_e32 v137, 0x42, v160
	v_cndmask_b32_e64 v145, v136, 0, s[42:43]
	v_mul_f32_e32 v136, v108, v135
	v_cmp_gt_i32_e32 vcc, v137, v122
	v_mul_f32_e32 v136, v136, v146
	s_and_b64 s[42:43], s[16:17], vcc
	v_add_u32_e32 v137, 0x43, v160
	v_cndmask_b32_e64 v146, v136, 0, s[42:43]
	v_mul_f32_e32 v136, v109, v135
	v_cmp_gt_i32_e32 vcc, v137, v122
	v_mul_f32_e32 v136, v136, v147
	s_and_b64 s[42:43], s[16:17], vcc
	v_cndmask_b32_e64 v147, v136, 0, s[42:43]
	v_add_u32_e32 v136, 0x50, v160
	v_mul_f32_e32 v137, v110, v135
	v_cmp_gt_i32_e32 vcc, v136, v122
	v_mul_f32_e32 v137, v137, v148
	s_and_b64 s[42:43], s[16:17], vcc
	v_cndmask_b32_e64 v148, v137, 0, s[42:43]
	v_add_u32_e32 v137, 0x51, v160
	v_mul_f32_e32 v136, v111, v135
	v_cmp_gt_i32_e32 vcc, v137, v122
	v_mul_f32_e32 v136, v136, v149
	s_and_b64 s[42:43], s[16:17], vcc
	v_add_u32_e32 v137, 0x52, v160
	v_cndmask_b32_e64 v149, v136, 0, s[42:43]
	v_mul_f32_e32 v136, v112, v135
	v_cmp_gt_i32_e32 vcc, v137, v122
	v_mul_f32_e32 v136, v136, v150
	s_and_b64 s[42:43], s[16:17], vcc
	v_add_u32_e32 v137, 0x53, v160
	v_cndmask_b32_e64 v150, v136, 0, s[42:43]
	v_mul_f32_e32 v136, v113, v135
	v_cmp_gt_i32_e32 vcc, v137, v122
	v_mul_f32_e32 v136, v136, v151
	s_and_b64 s[42:43], s[16:17], vcc
	v_cndmask_b32_e64 v151, v136, 0, s[42:43]
	v_add_u32_e32 v136, 0x60, v160
	v_mul_f32_e32 v137, v114, v135
	v_cmp_gt_i32_e32 vcc, v136, v122
	v_mul_f32_e32 v137, v137, v152
	s_and_b64 s[42:43], s[16:17], vcc
	v_cndmask_b32_e64 v152, v137, 0, s[42:43]
	v_add_u32_e32 v137, 0x61, v160
	v_mul_f32_e32 v136, v115, v135
	v_cmp_gt_i32_e32 vcc, v137, v122
	v_mul_f32_e32 v136, v136, v153
	s_and_b64 s[42:43], s[16:17], vcc
	v_add_u32_e32 v137, 0x62, v160
	v_cndmask_b32_e64 v153, v136, 0, s[42:43]
	v_mul_f32_e32 v136, v116, v135
	v_cmp_gt_i32_e32 vcc, v137, v122
	v_mul_f32_e32 v136, v136, v154
	s_and_b64 s[42:43], s[16:17], vcc
	v_add_u32_e32 v137, 0x63, v160
	v_cndmask_b32_e64 v154, v136, 0, s[42:43]
	v_mul_f32_e32 v136, v117, v135
	v_cmp_gt_i32_e32 vcc, v137, v122
	v_mul_f32_e32 v136, v136, v155
	s_and_b64 s[42:43], s[16:17], vcc
	v_cndmask_b32_e64 v155, v136, 0, s[42:43]
	v_add_u32_e32 v136, 0x70, v160
	v_mul_f32_e32 v137, v118, v135
	v_cmp_gt_i32_e32 vcc, v136, v122
	v_mul_f32_e32 v137, v137, v156
	s_and_b64 s[42:43], s[16:17], vcc
	v_cndmask_b32_e64 v156, v137, 0, s[42:43]
	v_add_u32_e32 v137, 0x71, v160
	v_mul_f32_e32 v136, v119, v135
	v_cmp_gt_i32_e32 vcc, v137, v122
	v_mul_f32_e32 v136, v136, v157
	s_and_b64 s[42:43], s[16:17], vcc
	v_add_u32_e32 v137, 0x72, v160
	v_cndmask_b32_e64 v157, v136, 0, s[42:43]
	v_mul_f32_e32 v136, v120, v135
	v_cmp_gt_i32_e32 vcc, v137, v122
	v_mul_f32_e32 v136, v136, v158
	s_and_b64 s[42:43], s[16:17], vcc
	v_cndmask_b32_e64 v158, v136, 0, s[42:43]
	v_add_u32_e32 v136, 0x73, v160
	v_mul_f32_e32 v135, v121, v135
	v_cmp_gt_i32_e32 vcc, v136, v122
	v_mul_f32_e32 v135, v135, v159
	s_and_b64 s[16:17], s[16:17], vcc
	v_cndmask_b32_e64 v135, v135, 0, s[16:17]
	v_cvt_pk_bf16_f32 v136, v66, v67
	v_cvt_pk_bf16_f32 v137, v68, v69
	v_cvt_pk_bf16_f32 v138, v70, v71
	v_cvt_pk_bf16_f32 v139, v72, v73
	v_cvt_pk_bf16_f32 v140, v161, v162
	v_cvt_pk_bf16_f32 v141, v163, v164
	v_cvt_pk_bf16_f32 v142, v165, v166
	v_cvt_pk_bf16_f32 v143, v167, v143
	v_cvt_pk_bf16_f32 v70, v144, v145
	v_cvt_pk_bf16_f32 v71, v146, v147
	v_cvt_pk_bf16_f32 v72, v148, v149
	v_cvt_pk_bf16_f32 v73, v150, v151
	v_cvt_pk_bf16_f32 v66, v152, v153
	v_cvt_pk_bf16_f32 v67, v154, v155
	v_cvt_pk_bf16_f32 v68, v156, v157
	v_cvt_pk_bf16_f32 v69, v158, v135
	v_add3_u32 v135, s40, v87, v127
	v_add_u32_e32 v176, 0x4800, v135
	v_add_u32_e32 v177, 0x5800, v135
	v_add_u32_e32 v178, 0x6800, v135
	v_add_u32_e32 v179, 0x7800, v135
	v_add_u32_e32 v180, 0x8800, v135
	v_add_u32_e32 v181, 0x9800, v135
	v_add_u32_e32 v182, 0xa800, v135
	v_add_u32_e32 v135, 0xb800, v135
	ds_read_b64 v[144:145], v176
	ds_read_b64 v[146:147], v176 offset:32
	ds_read_b64 v[148:149], v177 offset:256
	ds_read_b64 v[150:151], v177 offset:288
	ds_read_b64 v[152:153], v178 offset:512
	ds_read_b64 v[154:155], v178 offset:544
	ds_read_b64 v[156:157], v179 offset:768
	ds_read_b64 v[158:159], v179 offset:800
	ds_read_b64 v[160:161], v180 offset:1024
	ds_read_b64 v[162:163], v180 offset:1056
	ds_read_b64 v[164:165], v181 offset:1280
	ds_read_b64 v[166:167], v181 offset:1312
	ds_read_b64 v[168:169], v182 offset:1536
	ds_read_b64 v[170:171], v182 offset:1568
	ds_read_b64 v[172:173], v135 offset:1792
	ds_read_b64 v[174:175], v135 offset:1824
	s_setprio 1
	s_waitcnt lgkmcnt(14)
; template <int D, int DV, int MODE, int NMAP, int KT> ...
;     ...
;                 for (int b_ = 0; b_ < NVB; ++b_) {
;                     if (b_ + 1 < NVB) AT_VLOAD(b_ + 1, (b_ + 1) & 1);
;                     __builtin_amdgcn_sched_barrier(0);
;                     const int kk_ = b_ / NCB, c0_ = (b_ % NCB) * CBB;
;                     __builtin_amdgcn_s_setprio(1);
; #pragma unroll
;                     for (int x_ = 0; x_ < CBB; ++x_)
; #pragma unroll
;                         for (int mp = 0; mp < NMAP; ++mp) o[mp][c0_ + x_] = __builtin_amdgcn_mfma_f32_16x16x32_bf16(vfr[b_ & 1][x_], pb[mp][kk_], o[mp][c0_ + x_], 0, 0, 0);
;                     __builtin_amdgcn_s_setprio(0);
;                     __builtin_amdgcn_sched_barrier(0);
;                 }
	v_mfma_f32_16x16x32_bf16 v[30:33], v[144:147], v[136:139], v[30:33]
	s_waitcnt lgkmcnt(12)
	v_mfma_f32_16x16x32_bf16 v[26:29], v[148:151], v[136:139], v[26:29]
	s_waitcnt lgkmcnt(10)
	v_mfma_f32_16x16x32_bf16 v[22:25], v[152:155], v[136:139], v[22:25]
	s_waitcnt lgkmcnt(8)
	v_mfma_f32_16x16x32_bf16 v[18:21], v[156:159], v[136:139], v[18:21]
	s_setprio 0
	ds_read_b64 v[144:145], v176 offset:64
	ds_read_b64 v[146:147], v176 offset:96
	ds_read_b64 v[148:149], v177 offset:320
	ds_read_b64 v[150:151], v177 offset:352
	ds_read_b64 v[152:153], v178 offset:576
	ds_read_b64 v[154:155], v178 offset:608
	ds_read_b64 v[156:157], v179 offset:832
	ds_read_b64 v[158:159], v179 offset:864
	s_setprio 1
	s_waitcnt lgkmcnt(14)
	v_mfma_f32_16x16x32_bf16 v[14:17], v[160:163], v[136:139], v[14:17]
	s_waitcnt lgkmcnt(12)
	v_mfma_f32_16x16x32_bf16 v[10:13], v[164:167], v[136:139], v[10:13]
	s_waitcnt lgkmcnt(10)
	v_mfma_f32_16x16x32_bf16 v[6:9], v[168:171], v[136:139], v[6:9]
	s_waitcnt lgkmcnt(8)
	v_mfma_f32_16x16x32_bf16 v[2:5], v[172:175], v[136:139], v[2:5]
	s_setprio 0
	ds_read_b64 v[136:137], v180 offset:1088
	ds_read_b64 v[138:139], v180 offset:1120
	ds_read_b64 v[160:161], v181 offset:1344
	ds_read_b64 v[162:163], v181 offset:1376
	ds_read_b64 v[164:165], v182 offset:1600
	ds_read_b64 v[166:167], v182 offset:1632
	ds_read_b64 v[168:169], v135 offset:1856
	ds_read_b64 v[170:171], v135 offset:1888
	s_setprio 1
	s_waitcnt lgkmcnt(14)
	v_mfma_f32_16x16x32_bf16 v[30:33], v[144:147], v[140:143], v[30:33]
	s_waitcnt lgkmcnt(12)
	v_mfma_f32_16x16x32_bf16 v[26:29], v[148:151], v[140:143], v[26:29]
	s_waitcnt lgkmcnt(10)
	v_mfma_f32_16x16x32_bf16 v[22:25], v[152:155], v[140:143], v[22:25]
	s_waitcnt lgkmcnt(8)
	v_mfma_f32_16x16x32_bf16 v[18:21], v[156:159], v[140:143], v[18:21]
	s_setprio 0
	ds_read_b64 v[144:145], v176 offset:128
	ds_read_b64 v[146:147], v176 offset:160
	ds_read_b64 v[148:149], v177 offset:384
	ds_read_b64 v[150:151], v177 offset:416
	ds_read_b64 v[152:153], v178 offset:640
	ds_read_b64 v[154:155], v178 offset:672
	ds_read_b64 v[156:157], v179 offset:896
	ds_read_b64 v[158:159], v179 offset:928
	s_setprio 1
	s_waitcnt lgkmcnt(14)
	v_mfma_f32_16x16x32_bf16 v[14:17], v[136:139], v[140:143], v[14:17]
	s_waitcnt lgkmcnt(12)
	v_mfma_f32_16x16x32_bf16 v[10:13], v[160:163], v[140:143], v[10:13]
	s_waitcnt lgkmcnt(10)
	v_mfma_f32_16x16x32_bf16 v[6:9], v[164:167], v[140:143], v[6:9]
	s_waitcnt lgkmcnt(8)
	v_mfma_f32_16x16x32_bf16 v[2:5], v[168:171], v[140:143], v[2:5]
	s_setprio 0
	ds_read_b64 v[136:137], v180 offset:1152
	ds_read_b64 v[138:139], v180 offset:1184
	ds_read_b64 v[140:141], v181 offset:1408
	ds_read_b64 v[142:143], v181 offset:1440
	ds_read_b64 v[160:161], v182 offset:1664
	ds_read_b64 v[162:163], v182 offset:1696
	ds_read_b64 v[164:165], v135 offset:1920
	ds_read_b64 v[166:167], v135 offset:1952
	s_setprio 1
	s_waitcnt lgkmcnt(14)
	v_mfma_f32_16x16x32_bf16 v[30:33], v[144:147], v[70:73], v[30:33]
	s_waitcnt lgkmcnt(12)
	v_mfma_f32_16x16x32_bf16 v[26:29], v[148:151], v[70:73], v[26:29]
	s_waitcnt lgkmcnt(10)
	v_mfma_f32_16x16x32_bf16 v[22:25], v[152:155], v[70:73], v[22:25]
	s_waitcnt lgkmcnt(8)
	v_mfma_f32_16x16x32_bf16 v[18:21], v[156:159], v[70:73], v[18:21]
	s_setprio 0
	ds_read_b64 v[144:145], v176 offset:192
	ds_read_b64 v[146:147], v176 offset:224
	ds_read_b64 v[148:149], v177 offset:448
	ds_read_b64 v[150:151], v177 offset:480
	ds_read_b64 v[152:153], v178 offset:704
	ds_read_b64 v[154:155], v178 offset:736
	ds_read_b64 v[156:157], v179 offset:960
	ds_read_b64 v[158:159], v179 offset:992
	s_setprio 1
	s_waitcnt lgkmcnt(14)
	v_mfma_f32_16x16x32_bf16 v[14:17], v[136:139], v[70:73], v[14:17]
	s_waitcnt lgkmcnt(12)
	v_mfma_f32_16x16x32_bf16 v[10:13], v[140:143], v[70:73], v[10:13]
	s_waitcnt lgkmcnt(10)
	v_mfma_f32_16x16x32_bf16 v[6:9], v[160:163], v[70:73], v[6:9]
	s_waitcnt lgkmcnt(8)
	v_mfma_f32_16x16x32_bf16 v[2:5], v[164:167], v[70:73], v[2:5]
	s_setprio 0
	ds_read_b64 v[70:71], v180 offset:1216
	ds_read_b64 v[72:73], v180 offset:1248
	ds_read_b64 v[136:137], v181 offset:1472
	ds_read_b64 v[138:139], v181 offset:1504
	ds_read_b64 v[140:141], v182 offset:1728
	ds_read_b64 v[142:143], v182 offset:1760
	ds_read_b64 v[160:161], v135 offset:1984
	ds_read_b64 v[162:163], v135 offset:2016
	s_setprio 1
	s_waitcnt lgkmcnt(14)
	v_mfma_f32_16x16x32_bf16 v[30:33], v[144:147], v[66:69], v[30:33]
	s_waitcnt lgkmcnt(12)
	v_mfma_f32_16x16x32_bf16 v[26:29], v[148:151], v[66:69], v[26:29]
	s_waitcnt lgkmcnt(10)
	v_mfma_f32_16x16x32_bf16 v[22:25], v[152:155], v[66:69], v[22:25]
	s_waitcnt lgkmcnt(8)
	v_mfma_f32_16x16x32_bf16 v[18:21], v[156:159], v[66:69], v[18:21]
	s_setprio 0
	s_setprio 1
	s_waitcnt lgkmcnt(6)
	v_mfma_f32_16x16x32_bf16 v[14:17], v[70:73], v[66:69], v[14:17]
	s_waitcnt lgkmcnt(4)
	v_mfma_f32_16x16x32_bf16 v[10:13], v[136:139], v[66:69], v[10:13]
	s_waitcnt lgkmcnt(2)
	v_mfma_f32_16x16x32_bf16 v[6:9], v[140:143], v[66:69], v[6:9]
	s_waitcnt lgkmcnt(0)
	v_mfma_f32_16x16x32_bf16 v[2:5], v[160:163], v[66:69], v[2:5]
	s_setprio 0

; #define LAS __attribute__((address_space(3)))
; #define AT_SLOAD(bi_, sl_) do { _Pragma("unroll") for (int x_ = 0; x_ < NBB; ++x_) _Pragma("unroll") for (int kk = 0; kk < KD; ++kk) \
;                     kfr[sl_][x_][kk] = *(const LAS bf16x8*)(Ks + (((bi_) * NBB + x_) * 16 + r) * KSTR + mp * D + kk * 32 + g4 * 8); } while (0)
; template <int D, int DV, int MODE, int NMAP, int KT> ...
;     ...
;         if (MODE == 0 || kt * KT <= rowmin + 15) {
;             const LAS bf16_t* Ks = (const LAS bf16_t*)(lds + cur); const LAS bf16_t* Vt = (const LAS bf16_t*)(lds + cur + KS_BYTES);
;             const bool diag = (MODE != 0) && (kt * KT + KT - 1 > rowmin);
;             bf16x8 pb[NMAP][KK2];
;             f32x4 sall[NMAP][NB];
; #pragma unroll
;             for (int mp = 0; mp < NMAP; ++mp) {
;                 f32x4 (&s)[NB] = sall[mp];
;                 constexpr int KD = D / 32, NBB = (KD >= 8) ? 1 : (8 / KD), NSB = NB / NBB;
;                 bf16x8 kfr[2][NBB][KD];
;     ...
;                 AT_SLOAD(0, 0);
; #pragma unroll
;                 for (int bi = 0; bi < NSB; ++bi) {
;                     if (bi + 1 < NSB) AT_SLOAD(bi + 1, (bi + 1) & 1);
;                     __builtin_amdgcn_sched_barrier(0);
;                     __builtin_amdgcn_s_setprio(1);
; #pragma unroll
;                     for (int x_ = 0; x_ < NBB; ++x_) { const int nb = bi * NBB + x_;
;                         s[nb] = __builtin_amdgcn_mfma_f32_16x16x32_bf16(kfr[bi & 1][x_][0], qf[mp][0], (f32x4){0.f, 0.f, 0.f, 0.f}, 0, 0, 0);
; #pragma unroll
;                         for (int kk = 1; kk < KD; ++kk) s[nb] = __builtin_amdgcn_mfma_f32_16x16x32_bf16(kfr[bi & 1][x_][kk], qf[mp][kk], s[nb], 0, 0, 0); }
;                     __builtin_amdgcn_s_setprio(0);
;                     __builtin_amdgcn_sched_barrier(0);
;                 }
;     ...
;             }
; #pragma unroll
;             for (int mp = 0; mp < NMAP; ++mp) {
;                 f32x4 (&s)[NB] = sall[mp];
;                 if (MODE < 2) {
;                     if (diag) {
; #pragma unroll
;                         for (int nb = 0; nb < NB; ++nb)
; #pragma unroll
;                             for (int j = 0; j < 4; ++j) { if (kt * KT + nb * 16 + g4 * 4 + j > myrow) s[nb][j] = -INFINITY; }
.LBB0_1096:
	s_cmp_gt_i32 s76, s75
	s_cbranch_scc1 .LBB0_1106
	s_bitcmp1_b32 s2, 0
	s_cselect_b32 s2, 0x8c00, 0
	s_add_i32 s83, s2, 0
	v_lshlrev_b32_e32 v98, 1, v148
	v_add3_u32 v174, s83, v98, v151
	ds_read_b128 v[98:101], v174
	ds_read_b128 v[102:105], v174 offset:64
	ds_read_b128 v[106:109], v174 offset:4352
	ds_read_b128 v[110:113], v174 offset:4416
	ds_read_b128 v[114:117], v174 offset:8704
	ds_read_b128 v[118:121], v174 offset:8768
	ds_read_b128 v[158:161], v174 offset:13056
	ds_read_b128 v[162:165], v174 offset:13120
	s_add_i32 s2, s76, 63
	s_setprio 1
	s_waitcnt lgkmcnt(7)
	v_mfma_f32_16x16x32_bf16 v[98:101], v[98:101], v[2:5], 0
	s_waitcnt lgkmcnt(6)
	v_mfma_f32_16x16x32_bf16 v[126:129], v[102:105], v[6:9], v[98:101]
	s_waitcnt lgkmcnt(5)
	v_mfma_f32_16x16x32_bf16 v[98:101], v[106:109], v[2:5], 0
	s_waitcnt lgkmcnt(4)
	v_mfma_f32_16x16x32_bf16 v[122:125], v[110:113], v[6:9], v[98:101]
	s_waitcnt lgkmcnt(3)
	v_mfma_f32_16x16x32_bf16 v[98:101], v[114:117], v[2:5], 0
	s_waitcnt lgkmcnt(2)
	v_mfma_f32_16x16x32_bf16 v[118:121], v[118:121], v[6:9], v[98:101]
	s_waitcnt lgkmcnt(1)
	v_mfma_f32_16x16x32_bf16 v[98:101], v[158:161], v[2:5], 0
	s_waitcnt lgkmcnt(0)
	v_mfma_f32_16x16x32_bf16 v[106:109], v[162:165], v[6:9], v[98:101]
	s_setprio 0
	s_nop 5
	ds_read_b128 v[98:101], v174 offset:128
	ds_read_b128 v[102:105], v174 offset:192
	ds_read_b128 v[110:113], v174 offset:4480
	ds_read_b128 v[158:161], v174 offset:4544
	ds_read_b128 v[162:165], v174 offset:8832
	ds_read_b128 v[166:169], v174 offset:8896
	ds_read_b128 v[170:173], v174 offset:13184
	ds_read_b128 v[174:177], v174 offset:13248
	s_setprio 1
	s_waitcnt lgkmcnt(7)
	v_mfma_f32_16x16x32_bf16 v[98:101], v[98:101], v[10:13], 0
	s_waitcnt lgkmcnt(6)
	v_mfma_f32_16x16x32_bf16 v[114:117], v[102:105], v[14:17], v[98:101]
	s_waitcnt lgkmcnt(5)
	v_mfma_f32_16x16x32_bf16 v[98:101], v[110:113], v[10:13], 0
	s_waitcnt lgkmcnt(4)
	v_mfma_f32_16x16x32_bf16 v[110:113], v[158:161], v[14:17], v[98:101]
	s_waitcnt lgkmcnt(3)
	v_mfma_f32_16x16x32_bf16 v[98:101], v[162:165], v[10:13], 0
	s_waitcnt lgkmcnt(2)
	v_mfma_f32_16x16x32_bf16 v[102:105], v[166:169], v[14:17], v[98:101]
	s_waitcnt lgkmcnt(1)
	v_mfma_f32_16x16x32_bf16 v[98:101], v[170:173], v[10:13], 0
	s_waitcnt lgkmcnt(0)
	v_mfma_f32_16x16x32_bf16 v[98:101], v[174:177], v[14:17], v[98:101]
	s_setprio 0
	v_add_u32_e32 v171, s76, v150
	s_cmp_gt_i32 s2, s74
	v_add_u32_e32 v172, 2, v171
	v_add_u32_e32 v170, 3, v171
	v_add_u32_e32 v169, 16, v171
	v_add_u32_e32 v168, 17, v171
	v_add_u32_e32 v167, 18, v171
	v_add_u32_e32 v166, 19, v171
	v_add_u32_e32 v165, 32, v171
	v_add_u32_e32 v164, 33, v171
	v_add_u32_e32 v163, 34, v171
	v_add_u32_e32 v162, 35, v171
	v_add_u32_e32 v161, 48, v171
	v_add_u32_e32 v160, 49, v171
	v_add_u32_e32 v159, 50, v171
	v_add_u32_e32 v158, 51, v171
	s_cselect_b64 s[52:53], -1, 0
	s_cmp_le_i32 s2, s74
	v_cmp_gt_i32_e64 s[10:11], v171, v149
	v_cmp_lt_i32_e64 s[8:9], v171, v149
	v_cmp_le_i32_e64 s[28:29], v172, v149
	v_cmp_le_i32_e64 s[30:31], v170, v149
	v_cmp_gt_i32_e64 s[20:21], v169, v149
	v_cmp_le_i32_e64 s[22:23], v168, v149
	v_cmp_le_i32_e64 s[24:25], v167, v149
	v_cmp_le_i32_e64 s[26:27], v166, v149
	v_cmp_gt_i32_e64 s[12:13], v165, v149
	v_cmp_le_i32_e64 s[14:15], v164, v149
	v_cmp_le_i32_e64 s[16:17], v163, v149
	v_cmp_le_i32_e64 s[18:19], v162, v149
	v_cmp_gt_i32_e32 vcc, v161, v149
	v_cmp_le_i32_e64 s[2:3], v160, v149
	v_cmp_le_i32_e64 s[4:5], v159, v149
	v_cmp_le_i32_e64 s[6:7], v158, v149
	s_cbranch_scc1 .LBB0_1099
	v_mov_b32_e32 v174, s70
	v_cndmask_b32_e64 v173, v126, v174, s[10:11]
	v_cndmask_b32_e64 v126, v173, v126, s[8:9]
	v_cndmask_b32_e64 v127, v225, v127, s[8:9]
	v_cndmask_b32_e64 v128, v225, v128, s[28:29]
	v_cndmask_b32_e64 v129, v225, v129, s[30:31]
	v_cndmask_b32_e64 v122, v122, v174, s[20:21]
	v_cndmask_b32_e64 v123, v225, v123, s[22:23]
	v_cndmask_b32_e64 v124, v225, v124, s[24:25]
	v_cndmask_b32_e64 v125, v225, v125, s[26:27]
	v_cndmask_b32_e64 v118, v118, v174, s[12:13]
	v_cndmask_b32_e64 v119, v225, v119, s[14:15]
	v_cndmask_b32_e64 v120, v225, v120, s[16:17]
	v_cndmask_b32_e64 v121, v225, v121, s[18:19]
	v_cndmask_b32_e32 v106, v106, v174, vcc
	v_cndmask_b32_e64 v107, v225, v107, s[2:3]
	v_cndmask_b32_e64 v108, v225, v108, s[4:5]
	v_cndmask_b32_e64 v109, v225, v109, s[6:7]

; __device__ __forceinline__ unsigned cvt_pk_bf16(float lo, float hi) { unsigned r; asm volatile("v_cvt_pk_bf16_f32 %0, %1, %2" : "=v"(r) : "v"(lo), "v"(hi)); return r; }
; template <int D, int DV, int MODE, int NMAP, int KT> ...
;     ...
;                     const float nm = -m[mp]; float ps = 0.f;
; #pragma unroll
;                     for (int nb = 0; nb < NB; ++nb)
; #pragma unroll
;                         for (int j = 0; j < 4; ++j) { const float p = __builtin_amdgcn_exp2f(fmaf(s[nb][j], sc, nm)); ps += p; s[nb][j] = p; }
;                     l[mp] += ps;
;                 } else {
;                     const float rowf = __builtin_amdgcn_exp2f(l2g * (float)(myrow - kt * KT));
; #pragma unroll
;                     for (int nb = 0; nb < NB; ++nb)
; #pragma unroll
;                         for (int j = 0; j < 4; ++j) { float p = s[nb][j] * (rowf * ck[nb][j]); if (diag && (kt * KT + nb * 16 + g4 * 4 + j > myrow)) p = 0.f; s[nb][j] = p; }
;                 }
; #pragma unroll
;                 for (int kk = 0; kk < KK2; ++kk) { u32x4 wv; wv.x = cvt_pk_bf16(s[2 * kk][0], s[2 * kk][1]); wv.y = cvt_pk_bf16(s[2 * kk][2], s[2 * kk][3]);
;                     wv.z = cvt_pk_bf16(s[2 * kk + 1][0], s[2 * kk + 1][1]); wv.w = cvt_pk_bf16(s[2 * kk + 1][2], s[2 * kk + 1][3]); pb[mp][kk] = __builtin_bit_cast(bf16x8, wv); }
;             }
;             {
;                 constexpr int CBB = 4, NCB = (DV / 16) / CBB, NVB = KK2 * NCB;
;                 bf16x8 vfr[2][CBB];
;     ...
;                 AT_VLOAD(0, 0);
; #pragma unroll
;                 for (int b_ = 0; b_ < NVB; ++b_) {
;                     if (b_ + 1 < NVB) AT_VLOAD(b_ + 1, (b_ + 1) & 1);
;                     __builtin_amdgcn_sched_barrier(0);
;                     const int kk_ = b_ / NCB, c0_ = (b_ % NCB) * CBB;
;                     __builtin_amdgcn_s_setprio(1);
; #pragma unroll
;                     for (int x_ = 0; x_ < CBB; ++x_)
; #pragma unroll
;                         for (int mp = 0; mp < NMAP; ++mp) o[mp][c0_ + x_] = __builtin_amdgcn_mfma_f32_16x16x32_bf16(vfr[b_ & 1][x_], pb[mp][kk_], o[mp][c0_ + x_], 0, 0, 0);
;                     __builtin_amdgcn_s_setprio(0);
;                     __builtin_amdgcn_sched_barrier(0);
;                 }
.LBB0_1105:
	v_fma_f32 v114, v114, s71, -v0
	v_exp_f32_e32 v114, v114
	v_fma_f32 v115, v115, s71, -v0
	v_exp_f32_e32 v115, v115
	v_fma_f32 v116, v116, s71, -v0
	v_exp_f32_e32 v116, v116
	v_fma_f32 v117, v117, s71, -v0
	v_exp_f32_e32 v117, v117
	v_fma_f32 v110, v110, s71, -v0
	v_add_f32_e32 v122, 0, v114
	v_exp_f32_e32 v110, v110
	v_fma_f32 v111, v111, s71, -v0
	v_add_f32_e32 v122, v115, v122
	v_exp_f32_e32 v111, v111
	v_fma_f32 v112, v112, s71, -v0
	v_add_f32_e32 v122, v116, v122
	v_exp_f32_e32 v112, v112
	v_fma_f32 v113, v113, s71, -v0
	v_add_f32_e32 v122, v117, v122
	v_exp_f32_e32 v113, v113
	v_fma_f32 v102, v102, s71, -v0
	v_add_f32_e32 v122, v110, v122
	v_exp_f32_e32 v102, v102
	v_fma_f32 v103, v103, s71, -v0
	v_add_f32_e32 v122, v111, v122
	v_exp_f32_e32 v103, v103
	v_fma_f32 v104, v104, s71, -v0
	v_add_f32_e32 v122, v112, v122
	v_exp_f32_e32 v104, v104
	v_fma_f32 v105, v105, s71, -v0
	v_add_f32_e32 v122, v113, v122
	v_exp_f32_e32 v105, v105
	v_fma_f32 v98, v98, s71, -v0
	v_add_f32_e32 v122, v102, v122
	v_exp_f32_e32 v123, v98
	v_add_f32_e32 v122, v103, v122
	v_add_f32_e32 v122, v104, v122
	v_add_f32_e32 v122, v105, v122
	v_fma_f32 v99, v99, s71, -v0
	v_add_f32_e32 v98, v123, v122
	v_exp_f32_e32 v122, v99
	v_fma_f32 v99, v100, s71, -v0
	v_exp_f32_e32 v124, v99
	v_fma_f32 v99, v101, s71, -v0
	v_exp_f32_e32 v125, v99
	v_add_f32_e32 v98, v122, v98
	v_add_f32_e32 v98, v124, v98
	v_add3_u32 v170, s83, v148, v152
	v_add_f32_e32 v98, v125, v98
	v_add_u32_e32 v174, 0x4000, v170
	v_add_u32_e32 v175, 0x4800, v170
	v_add_u32_e32 v176, 0x5000, v170
	v_add_u32_e32 v177, 0x5800, v170
	v_add_u32_e32 v178, 0x6800, v170
	v_add_u32_e32 v179, 0x7000, v170
	v_add_u32_e32 v180, 0x7800, v170
	v_add_u32_e32 v181, 0x8000, v170
	v_add_f32_e32 v137, v137, v98
	v_cvt_pk_bf16_f32 v98, v114, v115
	v_cvt_pk_bf16_f32 v99, v116, v117
	v_cvt_pk_bf16_f32 v100, v110, v111
	v_cvt_pk_bf16_f32 v101, v112, v113
	v_cvt_pk_bf16_f32 v102, v102, v103
	v_cvt_pk_bf16_f32 v103, v104, v105
	v_cvt_pk_bf16_f32 v104, v123, v122
	v_cvt_pk_bf16_f32 v105, v124, v125
	ds_read_b64 v[110:111], v174 offset:1024
	ds_read_b64 v[112:113], v174 offset:1056
	ds_read_b64 v[114:115], v175 offset:1280
	ds_read_b64 v[116:117], v175 offset:1312
	ds_read_b64 v[122:123], v176 offset:1536
	ds_read_b64 v[124:125], v176 offset:1568
	ds_read_b64 v[126:127], v177 offset:1792
	ds_read_b64 v[128:129], v177 offset:1824
	ds_read_b64 v[158:159], v178
	ds_read_b64 v[160:161], v178 offset:32
	ds_read_b64 v[162:163], v179 offset:256
	ds_read_b64 v[164:165], v179 offset:288
	ds_read_b64 v[166:167], v180 offset:512
	ds_read_b64 v[168:169], v180 offset:544
	ds_read_b64 v[170:171], v181 offset:768
	ds_read_b64 v[172:173], v181 offset:800
	s_setprio 1
	s_waitcnt lgkmcnt(14)
	v_mfma_f32_16x16x32_bf16 v[90:93], v[110:113], v[118:121], v[90:93]
	v_mfma_f32_16x16x32_bf16 v[94:97], v[110:113], v[98:101], v[94:97]
	s_waitcnt lgkmcnt(12)
	v_mfma_f32_16x16x32_bf16 v[82:85], v[114:117], v[118:121], v[82:85]
	v_mfma_f32_16x16x32_bf16 v[86:89], v[114:117], v[98:101], v[86:89]
	s_waitcnt lgkmcnt(10)
	v_mfma_f32_16x16x32_bf16 v[74:77], v[122:125], v[118:121], v[74:77]
	v_mfma_f32_16x16x32_bf16 v[78:81], v[122:125], v[98:101], v[78:81]
	s_waitcnt lgkmcnt(8)
	v_mfma_f32_16x16x32_bf16 v[66:69], v[126:129], v[118:121], v[66:69]
	v_mfma_f32_16x16x32_bf16 v[70:73], v[126:129], v[98:101], v[70:73]
	s_setprio 0
	ds_read_b64 v[110:111], v174 offset:1088
	ds_read_b64 v[112:113], v174 offset:1120
	ds_read_b64 v[114:115], v175 offset:1344
	ds_read_b64 v[116:117], v175 offset:1376
	ds_read_b64 v[122:123], v176 offset:1600
	ds_read_b64 v[124:125], v176 offset:1632
	ds_read_b64 v[126:127], v177 offset:1856
	ds_read_b64 v[128:129], v177 offset:1888
	s_setprio 1
	s_waitcnt lgkmcnt(14)
	v_mfma_f32_16x16x32_bf16 v[50:53], v[158:161], v[118:121], v[50:53]
	v_mfma_f32_16x16x32_bf16 v[54:57], v[158:161], v[98:101], v[54:57]
	s_waitcnt lgkmcnt(12)
	v_mfma_f32_16x16x32_bf16 v[42:45], v[162:165], v[118:121], v[42:45]
	v_mfma_f32_16x16x32_bf16 v[46:49], v[162:165], v[98:101], v[46:49]
	s_waitcnt lgkmcnt(10)
	v_mfma_f32_16x16x32_bf16 v[34:37], v[166:169], v[118:121], v[34:37]
	v_mfma_f32_16x16x32_bf16 v[38:41], v[166:169], v[98:101], v[38:41]
	s_waitcnt lgkmcnt(8)
	v_mfma_f32_16x16x32_bf16 v[22:25], v[170:173], v[118:121], v[22:25]
	v_mfma_f32_16x16x32_bf16 v[26:29], v[170:173], v[98:101], v[26:29]
	s_setprio 0
	ds_read_b64 v[98:99], v178 offset:64
	ds_read_b64 v[100:101], v178 offset:96
	ds_read_b64 v[118:119], v179 offset:320
	ds_read_b64 v[120:121], v179 offset:352
	ds_read_b64 v[158:159], v180 offset:576
	ds_read_b64 v[160:161], v180 offset:608
	ds_read_b64 v[162:163], v181 offset:832
	ds_read_b64 v[164:165], v181 offset:864
	s_setprio 1
	s_waitcnt lgkmcnt(14)
	v_mfma_f32_16x16x32_bf16 v[90:93], v[110:113], v[106:109], v[90:93]
	v_mfma_f32_16x16x32_bf16 v[94:97], v[110:113], v[102:105], v[94:97]
	s_waitcnt lgkmcnt(12)
	v_mfma_f32_16x16x32_bf16 v[82:85], v[114:117], v[106:109], v[82:85]
	v_mfma_f32_16x16x32_bf16 v[86:89], v[114:117], v[102:105], v[86:89]
	s_waitcnt lgkmcnt(10)
	v_mfma_f32_16x16x32_bf16 v[74:77], v[122:125], v[106:109], v[74:77]
	v_mfma_f32_16x16x32_bf16 v[78:81], v[122:125], v[102:105], v[78:81]
	s_waitcnt lgkmcnt(8)
	v_mfma_f32_16x16x32_bf16 v[66:69], v[126:129], v[106:109], v[66:69]
	v_mfma_f32_16x16x32_bf16 v[70:73], v[126:129], v[102:105], v[70:73]
	s_setprio 0
	s_setprio 1
	s_waitcnt lgkmcnt(6)
	v_mfma_f32_16x16x32_bf16 v[50:53], v[98:101], v[106:109], v[50:53]
	v_mfma_f32_16x16x32_bf16 v[54:57], v[98:101], v[102:105], v[54:57]
	s_waitcnt lgkmcnt(4)
	v_mfma_f32_16x16x32_bf16 v[42:45], v[118:121], v[106:109], v[42:45]
	v_mfma_f32_16x16x32_bf16 v[46:49], v[118:121], v[102:105], v[46:49]
	s_waitcnt lgkmcnt(2)
	v_mfma_f32_16x16x32_bf16 v[34:37], v[158:161], v[106:109], v[34:37]
	v_mfma_f32_16x16x32_bf16 v[38:41], v[158:161], v[102:105], v[38:41]
	s_waitcnt lgkmcnt(0)
	v_mfma_f32_16x16x32_bf16 v[22:25], v[162:165], v[106:109], v[22:25]
	v_mfma_f32_16x16x32_bf16 v[26:29], v[162:165], v[102:105], v[26:29]
	s_setprio 0
